# v118 + top-k bit loop restructured: bound checks at loop bottom so every iteration (counted or skipped) costs one taken branch
# baseline (speedup 1.0000x reference)
; #define TK_GRP(g) { const int c0 = __popcll(__ballot(u[4 * (g)] >= cand)), c1 = __popcll(__ballot(u[4 * (g) + 1] >= cand)), c2 = __popcll(__ballot(u[4 * (g) + 2] >= cand)), c3 = __popcll(__ballot(u[4 * (g) + 3] >= cand)); cnt += (c0 + c1) + (c2 + c3); }
; __device__ __forceinline__ void indexer_unit(const Args& a, LAS unsigned char* lds, LAS unsigned long long* maskl, int b, int qblk, int wave, int lane) {
;     ...
;             unsigned T = 0u; bool exact = false; const int ng = (nr + 3) >> 2;
; #pragma unroll 1
;     ...
;                 const unsigned cand = T | (1u << bit); int cnt = 0;
;     ...
;                 switch (ng) {
;                     case 8: TK_GRP(7) [[fallthrough]];
;                     case 7: TK_GRP(6) [[fallthrough]];
;                     case 6: TK_GRP(5) [[fallthrough]];
;                     case 5: TK_GRP(4) [[fallthrough]];
;                     case 4: TK_GRP(3) [[fallthrough]];
;                     case 3: TK_GRP(2) [[fallthrough]];
;                     case 2: TK_GRP(1) [[fallthrough]];
;                     default: TK_GRP(0)
;                 }
;     ...
;                 if (cnt >= 256) { T = cand; if (cnt == 256) { exact = true; break; } }
;             }
.Ltk_bd_done:
	v_min_u32_e32 v30, v26, v27
	v_min_u32_e32 v31, v28, v29
	v_max_u32_e32 v25, v26, v27
	v_max_u32_e32 v26, v28, v29
	v_min_u32_e32 v30, v30, v31
	v_max_u32_e32 v25, v25, v26
	s_nop 1
	v_min_u32_dpp v31, v30, v30 quad_perm:[1,0,3,2] row_mask:0xf bank_mask:0xf
	v_max_u32_dpp v26, v25, v25 quad_perm:[1,0,3,2] row_mask:0xf bank_mask:0xf
	s_nop 1
	v_mov_b32_e32 v30, v31
	v_mov_b32_e32 v25, v26
	s_nop 1
	v_min_u32_dpp v31, v30, v30 quad_perm:[2,3,0,1] row_mask:0xf bank_mask:0xf
	v_max_u32_dpp v26, v25, v25 quad_perm:[2,3,0,1] row_mask:0xf bank_mask:0xf
	s_nop 1
	v_mov_b32_e32 v30, v31
	v_mov_b32_e32 v25, v26
	s_nop 1
	v_min_u32_dpp v31, v30, v30 row_half_mirror row_mask:0xf bank_mask:0xf
	v_max_u32_dpp v26, v25, v25 row_half_mirror row_mask:0xf bank_mask:0xf
	s_nop 1
	v_mov_b32_e32 v30, v31
	v_mov_b32_e32 v25, v26
	s_nop 1
	v_min_u32_dpp v31, v30, v30 row_mirror row_mask:0xf bank_mask:0xf
	v_max_u32_dpp v26, v25, v25 row_mirror row_mask:0xf bank_mask:0xf
	s_nop 1
	v_mov_b32_e32 v30, v31
	v_mov_b32_e32 v25, v26
	s_nop 1
	v_readlane_b32 s16, v25, 0
	v_readlane_b32 s17, v25, 16
	v_readlane_b32 s22, v25, 32
	v_readlane_b32 s23, v25, 48
	s_max_u32 s18, s16, s17
	s_max_u32 s22, s22, s23
	s_max_u32 s18, s18, s22
	v_readlane_b32 s16, v30, 0
	v_readlane_b32 s17, v30, 16
	v_readlane_b32 s22, v30, 32
	v_readlane_b32 s23, v30, 48
	s_min_u32 s16, s16, s17
	s_min_u32 s22, s22, s23
	s_min_u32 s23, s16, s22
	s_mov_b32 s10, 0
	s_mov_b32 s11, 32
.Ltk_nxt:
	s_add_i32 s11, s11, -1
	s_cmp_lt_i32 s11, 0
	s_cbranch_scc1 .Ltk_ties
	s_lshl_b32 s12, 1, s11
	s_or_b32 s13, s10, s12
	s_cmp_gt_u32 s13, s18
	s_cbranch_scc1 .Ltk_nxt
	s_cmp_le_u32 s13, s23
	s_cselect_b32 s10, s13, s10
	s_cbranch_scc1 .Ltk_nxt
	v_mov_b32_e32 v24, 0
	v_cmp_le_u32_e64 s[24:25], s13, v32
	v_cmp_le_u32_e64 s[26:27], s13, v33
	v_cmp_le_u32_e64 s[28:29], s13, v34
	v_cmp_le_u32_e64 s[30:31], s13, v35
	v_cmp_le_u32_e64 s[34:35], s13, v36
	v_cmp_le_u32_e64 s[36:37], s13, v37
	v_cmp_le_u32_e64 s[38:39], s13, v38
	v_cmp_le_u32_e64 s[40:41], s13, v39
	s_bcnt1_i32_b64 s42, s[24:25]
	s_bcnt1_i32_b64 s43, s[26:27]
	s_bcnt1_i32_b64 s44, s[28:29]
	s_bcnt1_i32_b64 s45, s[30:31]
	s_bcnt1_i32_b64 s46, s[34:35]
	s_bcnt1_i32_b64 s47, s[36:37]
	s_bcnt1_i32_b64 s48, s[38:39]
	s_bcnt1_i32_b64 s49, s[40:41]
	s_add_i32 s14, s42, s43
	s_add_i32 s14, s14, s44
	s_add_i32 s14, s14, s45
	v_add_u32_e32 v24, s46, v24
	v_add_u32_e32 v24, s47, v24
	v_add_u32_e32 v24, s48, v24
	v_add_u32_e32 v24, s49, v24
	s_cmp_lt_u32 s21, 2
	s_cbranch_scc1 .Ltk_dec
	v_cmp_le_u32_e64 s[24:25], s13, v40
	v_cmp_le_u32_e64 s[26:27], s13, v41
	v_cmp_le_u32_e64 s[28:29], s13, v42
	v_cmp_le_u32_e64 s[30:31], s13, v43
	v_cmp_le_u32_e64 s[34:35], s13, v44
	v_cmp_le_u32_e64 s[36:37], s13, v45
	v_cmp_le_u32_e64 s[38:39], s13, v46
	v_cmp_le_u32_e64 s[40:41], s13, v47
	s_bcnt1_i32_b64 s42, s[24:25]
	s_bcnt1_i32_b64 s43, s[26:27]
	s_bcnt1_i32_b64 s44, s[28:29]
	s_bcnt1_i32_b64 s45, s[30:31]
	s_bcnt1_i32_b64 s46, s[34:35]
	s_bcnt1_i32_b64 s47, s[36:37]
	s_bcnt1_i32_b64 s48, s[38:39]
	s_bcnt1_i32_b64 s49, s[40:41]
	s_add_i32 s14, s14, s42
	s_add_i32 s14, s14, s43
	s_add_i32 s14, s14, s44
	s_add_i32 s14, s14, s45
	v_add_u32_e32 v24, s46, v24
	v_add_u32_e32 v24, s47, v24
	v_add_u32_e32 v24, s48, v24
	v_add_u32_e32 v24, s49, v24
	s_cmp_lt_u32 s21, 3
	s_cbranch_scc1 .Ltk_dec
	v_cmp_le_u32_e64 s[24:25], s13, v48
	v_cmp_le_u32_e64 s[26:27], s13, v49
	v_cmp_le_u32_e64 s[28:29], s13, v50
	v_cmp_le_u32_e64 s[30:31], s13, v51
	v_cmp_le_u32_e64 s[34:35], s13, v52
	v_cmp_le_u32_e64 s[36:37], s13, v53
	v_cmp_le_u32_e64 s[38:39], s13, v54
	v_cmp_le_u32_e64 s[40:41], s13, v55
	s_bcnt1_i32_b64 s42, s[24:25]
	s_bcnt1_i32_b64 s43, s[26:27]
	s_bcnt1_i32_b64 s44, s[28:29]
	s_bcnt1_i32_b64 s45, s[30:31]
	s_bcnt1_i32_b64 s46, s[34:35]
	s_bcnt1_i32_b64 s47, s[36:37]
	s_bcnt1_i32_b64 s48, s[38:39]
	s_bcnt1_i32_b64 s49, s[40:41]
	s_add_i32 s14, s14, s42
	s_add_i32 s14, s14, s43
	s_add_i32 s14, s14, s44
	s_add_i32 s14, s14, s45
	v_add_u32_e32 v24, s46, v24
	v_add_u32_e32 v24, s47, v24
	v_add_u32_e32 v24, s48, v24
	v_add_u32_e32 v24, s49, v24
	s_cmp_lt_u32 s21, 4
	s_cbranch_scc1 .Ltk_dec
	v_cmp_le_u32_e64 s[24:25], s13, v56
	v_cmp_le_u32_e64 s[26:27], s13, v57
	v_cmp_le_u32_e64 s[28:29], s13, v58
	v_cmp_le_u32_e64 s[30:31], s13, v59
	v_cmp_le_u32_e64 s[34:35], s13, v60
	v_cmp_le_u32_e64 s[36:37], s13, v61
	v_cmp_le_u32_e64 s[38:39], s13, v62
	v_cmp_le_u32_e64 s[40:41], s13, v63
	s_bcnt1_i32_b64 s42, s[24:25]
	s_bcnt1_i32_b64 s43, s[26:27]
	s_bcnt1_i32_b64 s44, s[28:29]
	s_bcnt1_i32_b64 s45, s[30:31]
	s_bcnt1_i32_b64 s46, s[34:35]
	s_bcnt1_i32_b64 s47, s[36:37]
	s_bcnt1_i32_b64 s48, s[38:39]
	s_bcnt1_i32_b64 s49, s[40:41]
	s_add_i32 s14, s14, s42
	s_add_i32 s14, s14, s43
	s_add_i32 s14, s14, s44
	s_add_i32 s14, s14, s45
	v_add_u32_e32 v24, s46, v24
	v_add_u32_e32 v24, s47, v24
	v_add_u32_e32 v24, s48, v24
	v_add_u32_e32 v24, s49, v24

; __device__ __forceinline__ void indexer_unit(const Args& a, LAS unsigned char* lds, LAS unsigned long long* maskl, int b, int qblk, int wave, int lane) {
;     ...
;             int need = 0; const unsigned long long lt = (1ull << lane) - 1ull;
;             if (!exact) {
;                 int cl = 0;
; #pragma unroll
;                 for (int r = 0; r < 32; ++r) cl += (u[r] > T) ? 1 : 0;
;                 int ngt = 0;
; #pragma unroll
;                 for (int bb = 0; bb < 6; ++bb) ngt += __popcll(__ballot((cl >> bb) & 1)) << bb;
;                 need = 256 - ngt;
.Ltk_ties:
	v_mov_b32_e32 v100, 0
	v_mov_b32_e32 v101, 0
	v_mov_b32_e32 v24, 0
	v_cmp_lt_u32_e64 s[24:25], s10, v32
	v_cmp_lt_u32_e64 s[26:27], s10, v33
	v_cmp_lt_u32_e64 s[28:29], s10, v34
	v_cmp_lt_u32_e64 s[30:31], s10, v35
	v_cmp_lt_u32_e64 s[34:35], s10, v36
	v_cmp_lt_u32_e64 s[36:37], s10, v37
	v_cmp_lt_u32_e64 s[38:39], s10, v38
	v_cmp_lt_u32_e64 s[40:41], s10, v39
	s_bcnt1_i32_b64 s42, s[24:25]
	s_bcnt1_i32_b64 s43, s[26:27]
	s_bcnt1_i32_b64 s44, s[28:29]
	s_bcnt1_i32_b64 s45, s[30:31]
	s_bcnt1_i32_b64 s46, s[34:35]
	s_bcnt1_i32_b64 s47, s[36:37]
	s_bcnt1_i32_b64 s48, s[38:39]
	s_bcnt1_i32_b64 s49, s[40:41]
	s_add_i32 s14, s42, s43
	s_add_i32 s14, s14, s44
	s_add_i32 s14, s14, s45
	v_add_u32_e32 v24, s46, v24
	v_add_u32_e32 v24, s47, v24
	v_add_u32_e32 v24, s48, v24
	v_add_u32_e32 v24, s49, v24
	s_cmp_lt_u32 s21, 2
	s_cbranch_scc1 .Ltk_tie_cnt_done
	v_cmp_lt_u32_e64 s[24:25], s10, v40
	v_cmp_lt_u32_e64 s[26:27], s10, v41
	v_cmp_lt_u32_e64 s[28:29], s10, v42
	v_cmp_lt_u32_e64 s[30:31], s10, v43
	v_cmp_lt_u32_e64 s[34:35], s10, v44
	v_cmp_lt_u32_e64 s[36:37], s10, v45
	v_cmp_lt_u32_e64 s[38:39], s10, v46
	v_cmp_lt_u32_e64 s[40:41], s10, v47
	s_bcnt1_i32_b64 s42, s[24:25]
	s_bcnt1_i32_b64 s43, s[26:27]
	s_bcnt1_i32_b64 s44, s[28:29]
	s_bcnt1_i32_b64 s45, s[30:31]
	s_bcnt1_i32_b64 s46, s[34:35]
	s_bcnt1_i32_b64 s47, s[36:37]
	s_bcnt1_i32_b64 s48, s[38:39]
	s_bcnt1_i32_b64 s49, s[40:41]
	s_add_i32 s14, s14, s42
	s_add_i32 s14, s14, s43
	s_add_i32 s14, s14, s44
	s_add_i32 s14, s14, s45
	v_add_u32_e32 v24, s46, v24
	v_add_u32_e32 v24, s47, v24
	v_add_u32_e32 v24, s48, v24
	v_add_u32_e32 v24, s49, v24
	s_cmp_lt_u32 s21, 3
	s_cbranch_scc1 .Ltk_tie_cnt_done
	v_cmp_lt_u32_e64 s[24:25], s10, v48
	v_cmp_lt_u32_e64 s[26:27], s10, v49
	v_cmp_lt_u32_e64 s[28:29], s10, v50
	v_cmp_lt_u32_e64 s[30:31], s10, v51
	v_cmp_lt_u32_e64 s[34:35], s10, v52
	v_cmp_lt_u32_e64 s[36:37], s10, v53
	v_cmp_lt_u32_e64 s[38:39], s10, v54
	v_cmp_lt_u32_e64 s[40:41], s10, v55
	s_bcnt1_i32_b64 s42, s[24:25]
	s_bcnt1_i32_b64 s43, s[26:27]
	s_bcnt1_i32_b64 s44, s[28:29]
	s_bcnt1_i32_b64 s45, s[30:31]
	s_bcnt1_i32_b64 s46, s[34:35]
	s_bcnt1_i32_b64 s47, s[36:37]
	s_bcnt1_i32_b64 s48, s[38:39]
	s_bcnt1_i32_b64 s49, s[40:41]
	s_add_i32 s14, s14, s42
	s_add_i32 s14, s14, s43
	s_add_i32 s14, s14, s44
	s_add_i32 s14, s14, s45
	v_add_u32_e32 v24, s46, v24
	v_add_u32_e32 v24, s47, v24
	v_add_u32_e32 v24, s48, v24
	v_add_u32_e32 v24, s49, v24
	s_cmp_lt_u32 s21, 4
	s_cbranch_scc1 .Ltk_tie_cnt_done
	v_cmp_lt_u32_e64 s[24:25], s10, v56
	v_cmp_lt_u32_e64 s[26:27], s10, v57
	v_cmp_lt_u32_e64 s[28:29], s10, v58
	v_cmp_lt_u32_e64 s[30:31], s10, v59
	v_cmp_lt_u32_e64 s[34:35], s10, v60
	v_cmp_lt_u32_e64 s[36:37], s10, v61
	v_cmp_lt_u32_e64 s[38:39], s10, v62
	v_cmp_lt_u32_e64 s[40:41], s10, v63
	s_bcnt1_i32_b64 s42, s[24:25]
	s_bcnt1_i32_b64 s43, s[26:27]
	s_bcnt1_i32_b64 s44, s[28:29]
	s_bcnt1_i32_b64 s45, s[30:31]
	s_bcnt1_i32_b64 s46, s[34:35]
	s_bcnt1_i32_b64 s47, s[36:37]
	s_bcnt1_i32_b64 s48, s[38:39]
	s_bcnt1_i32_b64 s49, s[40:41]
	s_add_i32 s14, s14, s42
	s_add_i32 s14, s14, s43
	s_add_i32 s14, s14, s44
	s_add_i32 s14, s14, s45
	v_add_u32_e32 v24, s46, v24
	v_add_u32_e32 v24, s47, v24
	v_add_u32_e32 v24, s48, v24
	v_add_u32_e32 v24, s49, v24
